# chain dma+stores plus gla_prep task loop: the two full vmcnt(0) drains per task become counted waits (vmcnt(17) before dir loop when a next task was prefetched, vmcnt(16) at task top)
# speedup vs baseline: 1.0173x; 1.0173x over previous
; #define LAS __attribute__((address_space(3)))
; DI void phase_gla_prep(const Params& P, int l, int bid, int nb, LAS unsigned char* lds) {
;     const int tid = threadIdx.x, wid = tid >> 6, lane = tid & 63, dpl = lane & 7, rg = lane >> 3, r32 = lane & 31, hi = lane >> 5;
;     const bf16_t* PG = (const bf16_t*)(P.ws + WS_PG); const float* LR = (const float*)(P.ws + WS_LR);
;     const int c0 = wid * 16 + dpl * 2;
;     const int p0 = (c0 & ~15) | (c0 & 3) | ((c0 & 4) << 1) | ((c0 & 8) >> 1);
;     ...
;         { const int dir = wid >> 2, ti = (wid >> 1) & 1, tj = wid & 1; const int i = ti * 32 + r32, jr = tj * 32 + r32;
;           f32x16 acc; for (int x = 0; x < 16; ++x) acc[x] = 0.f;
; #pragma unroll
;           for (int s = 0; s < 8; ++s) { const int ch = 2 * s + hi;
;               const bf16x8 a = *(const LAS bf16x8*)(lds + PP_KD + dir * 16384 + jr * 256 + ((ch ^ (jr & 15)) << 4));
;               const bf16x8 b = *(const LAS bf16x8*)(lds + PP_QD + dir * 16384 + i * 256 + ((ch ^ (i & 15)) << 4));
;               acc = __builtin_amdgcn_mfma_f32_32x32x16_bf16(a, b, acc, 0, 0, 0); }
;           unsigned char* am = P.ws + GL_PD + ((size_t)dir * 2560 + task) * GL_PD_BYTES + 16384;
; #pragma unroll
;           for (int a4 = 0; a4 < 4; ++a4) { float v[4];
; #pragma unroll
;               for (int b4 = 0; b4 < 4; ++b4) { const int j = tj * 32 + 8 * a4 + 4 * hi + b4; const bool keep = dir ? (j >= i) : (j <= i); v[b4] = keep ? acc[a4 * 4 + b4] : 0.f; }
.LBB0_332:
	s_cmp_lt_i32 s72, 3
	s_cselect_b64 s[0:1], -1, 0
	s_cmp_gt_i32 s73, 2
	s_cselect_b64 s[2:3], -1, 0
	s_and_b64 s[0:1], s[0:1], s[2:3]
	s_andn2_b64 vcc, exec, s[0:1]
	s_cbranch_vccnz .LBB0_400
	s_cmpk_gt_i32 s33, 0x9ff
	v_and_b32_e32 v136, 0x3ff, v0
	s_cbranch_scc1 .LBB0_350
	v_lshrrev_b32_e32 v137, 6, v136
	v_and_b32_e32 v138, 7, v136
	v_lshlrev_b32_e32 v3, 2, v136
	v_lshlrev_b32_e32 v2, 4, v137
	v_and_or_b32 v4, v3, 8, v2
	v_lshlrev_b32_e32 v5, 1, v138
	v_and_b32_e32 v6, 4, v136
	v_bfe_u32 v9, v136, 3, 3
	v_and_or_b32 v6, v5, 2, v6
	v_lshrrev_b32_e32 v10, 3, v4
	v_bitop3_b32 v4, v9, v136, 7 bitop3:0x78
	s_add_u32 s74, s50, 0x10440000
	v_or_b32_e32 v8, v2, v5
	v_and_b32_e32 v5, 31, v136
	v_lshlrev_b32_e32 v11, 1, v6
	v_lshlrev_b32_e32 v32, 4, v4
	v_bfe_u32 v4, v136, 6, 1
	v_lshrrev_b32_e32 v6, 2, v136
	s_addc_u32 s75, s51, 0
	v_and_or_b32 v9, v6, 32, v5
	v_lshlrev_b32_e32 v6, 5, v4
	s_add_u32 s44, s50, 0x1f440000
	v_lshlrev_b32_e32 v2, 3, v5
	v_lshrrev_b32_e32 v12, 8, v136
	v_or_b32_e32 v5, v6, v5
	s_addc_u32 s45, s51, 0
	v_lshlrev_b32_e32 v13, 14, v12
	s_add_i32 s2, 0, 0x12000
	v_lshlrev_b32_e32 v5, 8, v5
	v_bfe_u32 v139, v136, 5, 1
	v_add3_u32 v140, s2, v13, v5
	v_lshlrev_b32_e32 v5, 8, v9
	v_add3_u32 v141, 0, v13, v5
	v_lshl_or_b32 v13, v139, 2, v6
	v_lshlrev_b32_e32 v6, 2, v8
	s_add_i32 s2, 0, 0x1a200
	v_add_u32_e32 v143, s2, v6
	s_add_i32 s2, 0, 0x1a400
	v_add_u32_e32 v144, s2, v6
	s_add_i32 s2, 0, 0x1a600
	v_add_u32_e32 v145, s2, v6
	s_add_i32 s2, 0, 0x1a800
	v_add_u32_e32 v146, s2, v6
	s_add_i32 s2, 0, 0x1aa00
	v_add_u32_e32 v147, s2, v6
	s_add_i32 s2, 0, 0x1ac00
	v_add_u32_e32 v148, s2, v6
	s_add_i32 s2, 0, 0x1ae00
	v_add_u32_e32 v149, s2, v6
	s_add_i32 s2, 0, 0x1b000
	v_add_u32_e32 v150, s2, v6
	s_add_i32 s2, 0, 0x1b200
	v_add_u32_e32 v151, s2, v6
	s_add_i32 s2, 0, 0x1b400
	v_add_u32_e32 v152, s2, v6
	s_add_i32 s2, 0, 0x1b600
	v_add_u32_e32 v153, s2, v6
	s_add_i32 s2, 0, 0x1b800
	v_add_u32_e32 v154, s2, v6
	s_add_i32 s2, 0, 0x1ba00
	v_add_u32_e32 v155, s2, v6
	s_add_i32 s2, 0, 0x1bc00
	v_and_b32_e32 v7, 63, v136
	v_and_b32_e32 v64, 56, v136
	v_add_u32_e32 v156, s2, v6
	s_add_i32 s2, 0, 0x1be00
	v_lshlrev_b32_e32 v24, 1, v8
	v_lshlrev_b32_e32 v30, 7, v8
	v_cmp_gt_u32_e64 s[0:1], 8, v7
	v_add_u32_e32 v157, s2, v6
	v_cmp_gt_u32_e64 s[2:3], 56, v7
	v_cmp_gt_u32_e64 s[4:5], 48, v7
	v_cmp_gt_u32_e64 s[6:7], 32, v7
	v_cmp_gt_u32_e64 s[8:9], 16, v7
	v_bitop3_b32 v7, v10, v136, 8 bitop3:0x78
	v_lshl_or_b32 v8, v64, 8, v11
	v_lshl_add_u32 v158, v7, 4, v8
	v_or_b32_e32 v7, 1, v64
	v_bitop3_b32 v8, v10, v7, 9 bitop3:0x78
	v_lshl_or_b32 v7, v7, 8, v11
	v_lshl_add_u32 v159, v8, 4, v7
	v_or_b32_e32 v7, 2, v64
	v_bitop3_b32 v8, v10, v7, 10 bitop3:0x78
	v_lshl_or_b32 v7, v7, 8, v11
	v_lshl_add_u32 v160, v8, 4, v7
	v_or_b32_e32 v7, 3, v64
	v_bitop3_b32 v8, v10, v7, 11 bitop3:0x78
	v_lshl_or_b32 v7, v7, 8, v11
	v_lshl_add_u32 v161, v8, 4, v7
	v_or_b32_e32 v7, 4, v64
	v_bitop3_b32 v8, v10, v7, 12 bitop3:0x78
	v_lshl_or_b32 v7, v7, 8, v11
	v_lshl_add_u32 v162, v8, 4, v7
	v_or_b32_e32 v7, 5, v64
	v_bitop3_b32 v8, v10, v7, 13 bitop3:0x78
	v_lshl_or_b32 v7, v7, 8, v11
	v_lshl_add_u32 v163, v8, 4, v7
	v_or_b32_e32 v7, 6, v64
	v_bitop3_b32 v8, v10, v7, 14 bitop3:0x78
	v_lshl_or_b32 v7, v7, 8, v11
	v_lshl_add_u32 v164, v8, 4, v7
	v_or_b32_e32 v7, 7, v64
	v_bitop3_b32 v8, v10, v7, 15 bitop3:0x78
	v_lshl_or_b32 v7, v7, 8, v11
	v_and_b32_e32 v14, 15, v136
	v_lshl_add_u32 v165, v8, 4, v7
	v_bitop3_b32 v7, v139, v136, 15 bitop3:0x78
	v_lshlrev_b32_e32 v166, 4, v7
	v_bitop3_b32 v7, v139, v14, 2 bitop3:0x36
	v_lshlrev_b32_e32 v167, 4, v7
	v_bitop3_b32 v7, v139, v14, 4 bitop3:0x36
	v_lshlrev_b32_e32 v168, 4, v7
	v_bitop3_b32 v7, v139, v14, 6 bitop3:0x36
	v_lshlrev_b32_e32 v169, 4, v7
	v_bitop3_b32 v7, v139, v14, 8 bitop3:0x36
	v_lshlrev_b32_e32 v170, 4, v7
	v_bitop3_b32 v7, v139, v14, 10 bitop3:0x36
	v_lshlrev_b32_e32 v171, 4, v7
	v_bitop3_b32 v7, v139, v14, 12 bitop3:0x36
	v_lshlrev_b32_e32 v172, 4, v7
	v_bitop3_b32 v7, v139, v14, 14 bitop3:0x36
	v_cmp_le_u32_e32 vcc, v13, v9
	s_movk_i32 s10, 0x100
	v_lshlrev_b32_e32 v173, 4, v7
	v_cndmask_b32_e64 v7, 0, 1, vcc
	v_cmp_ge_u32_e32 vcc, v13, v9
	v_cmp_lt_u32_e64 s[12:13], v13, v9
	v_lshlrev_b32_e32 v15, 2, v4
	v_cndmask_b32_e64 v8, 0, 1, vcc
	v_cmp_gt_u32_e32 vcc, s10, v136
	v_lshrrev_b32_e32 v65, 1, v136
	v_lshlrev_b32_e32 v17, 3, v139
	v_cndmask_b32_e32 v7, v8, v7, vcc
	v_and_b32_e32 v7, 1, v7
	v_cmp_eq_u32_e64 s[10:11], 1, v7
	v_or_b32_e32 v7, 1, v13
	v_cndmask_b32_e64 v8, 0, 1, s[12:13]
	v_cmp_ge_u32_e64 s[12:13], v7, v9
	v_bfe_u32 v16, v136, 1, 3
	v_add_u32_e32 v76, 0x200, v136
	v_cndmask_b32_e64 v7, 0, 1, s[12:13]
	v_cndmask_b32_e32 v7, v7, v8, vcc
	v_and_b32_e32 v7, 1, v7
	v_cmp_eq_u32_e64 s[12:13], 1, v7
	v_or_b32_e32 v7, 2, v13
	v_cmp_le_u32_e64 s[14:15], v7, v9
	s_add_i32 s70, 0, 0x1a000
	v_add_u32_e32 v81, 0x600, v136
	v_cndmask_b32_e64 v8, 0, 1, s[14:15]
	v_cmp_ge_u32_e64 s[14:15], v7, v9
	s_add_u32 s78, s50, 0x29e70000
	s_addc_u32 s79, s51, 0
	v_cndmask_b32_e64 v7, 0, 1, s[14:15]
	v_cndmask_b32_e32 v7, v7, v8, vcc
	v_and_b32_e32 v7, 1, v7
	v_cmp_eq_u32_e64 s[14:15], 1, v7
	v_or_b32_e32 v7, 3, v13
	v_cmp_le_u32_e64 s[16:17], v7, v9
	s_lshl_b32 s76, s33, 8
	s_and_b32 s76, s76, 0x300
	v_cndmask_b32_e64 v8, 0, 1, s[16:17]
	v_cmp_ge_u32_e64 s[16:17], v7, v9
	s_add_u32 s80, s74, s76
	v_mov_b32_e32 v25, 0
	v_cndmask_b32_e64 v7, 0, 1, s[16:17]
	v_cndmask_b32_e32 v7, v7, v8, vcc
	v_and_b32_e32 v7, 1, v7
	v_cmp_eq_u32_e64 s[16:17], 1, v7
	v_bitop3_b32 v7, v15, v65, 7 bitop3:0x78
	v_lshl_or_b32 v38, v7, 4, v17
	v_or_b32_e32 v7, 8, v13
	v_cmp_le_u32_e64 s[18:19], v7, v9
	s_addc_u32 s81, s75, 0
; #define LAS __attribute__((address_space(3)))
; DI void phase_gla_prep(const Params& P, int l, int bid, int nb, LAS unsigned char* lds) {
;     ...
;         { const int dir = wid >> 2, ti = (wid >> 1) & 1, tj = wid & 1; const int i = ti * 32 + r32, jr = tj * 32 + r32;
;           f32x16 acc; for (int x = 0; x < 16; ++x) acc[x] = 0.f;
; #pragma unroll
;           for (int s = 0; s < 8; ++s) { const int ch = 2 * s + hi;
;               const bf16x8 a = *(const LAS bf16x8*)(lds + PP_KD + dir * 16384 + jr * 256 + ((ch ^ (jr & 15)) << 4));
;               const bf16x8 b = *(const LAS bf16x8*)(lds + PP_QD + dir * 16384 + i * 256 + ((ch ^ (i & 15)) << 4));
;               acc = __builtin_amdgcn_mfma_f32_32x32x16_bf16(a, b, acc, 0, 0, 0); }
;           unsigned char* am = P.ws + GL_PD + ((size_t)dir * 2560 + task) * GL_PD_BYTES + 16384;
; #pragma unroll
;           for (int a4 = 0; a4 < 4; ++a4) { float v[4];
; #pragma unroll
;               for (int b4 = 0; b4 < 4; ++b4) { const int j = tj * 32 + 8 * a4 + 4 * hi + b4; const bool keep = dir ? (j >= i) : (j <= i); v[b4] = keep ? acc[a4 * 4 + b4] : 0.f; }
	v_mul_u32_u24_e32 v34, 0xa00, v12
	v_cndmask_b32_e64 v8, 0, 1, s[18:19]
	v_cmp_ge_u32_e64 s[18:19], v7, v9
	v_lshlrev_b32_e32 v83, 12, v12
	v_lshlrev_b32_e32 v56, 12, v64
	v_cndmask_b32_e64 v7, 0, 1, s[18:19]
	v_cndmask_b32_e32 v7, v7, v8, vcc
	v_and_b32_e32 v7, 1, v7
	v_cmp_eq_u32_e64 s[18:19], 1, v7
	v_or_b32_e32 v7, 9, v13
	v_cmp_le_u32_e64 s[20:21], v7, v9
	v_mov_b32_e32 v57, v25
	s_movk_i32 s76, 0x1000
	v_cndmask_b32_e64 v8, 0, 1, s[20:21]
	v_cmp_ge_u32_e64 s[20:21], v7, v9
	v_lshlrev_b32_e32 v22, 4, v136
	v_mov_b32_e32 v23, v25
	v_cndmask_b32_e64 v7, 0, 1, s[20:21]
	v_cndmask_b32_e32 v7, v7, v8, vcc
	v_and_b32_e32 v7, 1, v7
	v_cmp_eq_u32_e64 s[20:21], 1, v7
	v_or_b32_e32 v7, 10, v13
	v_cmp_le_u32_e64 s[22:23], v7, v9
	v_lshl_add_u64 v[26:27], s[44:45], 0, v[22:23]
	v_and_b32_e32 v4, 0xff, v136
	v_cndmask_b32_e64 v8, 0, 1, s[22:23]
	v_cmp_ge_u32_e64 s[22:23], v7, v9
	v_add_u32_e32 v142, s70, v6
	v_lshl_add_u32 v79, v4, 1, 0
	v_cndmask_b32_e64 v7, 0, 1, s[22:23]
	v_cndmask_b32_e32 v7, v7, v8, vcc
	v_and_b32_e32 v7, 1, v7
	v_cmp_eq_u32_e64 s[22:23], 1, v7
	v_or_b32_e32 v7, 11, v13
	v_cmp_le_u32_e64 s[24:25], v7, v9
	v_lshlrev_b32_e32 v4, 7, v4
	v_mov_b32_e32 v5, v25
	v_cndmask_b32_e64 v8, 0, 1, s[24:25]
	v_cmp_ge_u32_e64 s[24:25], v7, v9
	v_lshl_add_u32 v175, v64, 7, 0
	v_lshl_add_u64 v[4:5], s[50:51], 0, v[4:5]
	v_cndmask_b32_e64 v7, 0, 1, s[24:25]
	v_cndmask_b32_e32 v7, v7, v8, vcc
	v_and_b32_e32 v7, 1, v7
	v_cmp_eq_u32_e64 s[24:25], 1, v7
	v_bitop3_b32 v7, v15, v16, 1 bitop3:0x36
	v_lshl_or_b32 v40, v7, 4, v17
	v_or_b32_e32 v7, 16, v13
	v_cmp_le_u32_e64 s[26:27], v7, v9
	v_and_b32_e32 v78, 0x7f, v136
	s_movk_i32 s71, 0x200
	v_cndmask_b32_e64 v8, 0, 1, s[26:27]
	v_cmp_ge_u32_e64 s[26:27], v7, v9
	v_lshl_add_u64 v[66:67], s[78:79], 0, v[22:23]
	v_add_u32_e32 v180, s70, v3
	v_cndmask_b32_e64 v7, 0, 1, s[26:27]
	v_cndmask_b32_e32 v7, v7, v8, vcc
	v_and_b32_e32 v7, 1, v7
	v_cmp_eq_u32_e64 s[26:27], 1, v7
	v_or_b32_e32 v7, 17, v13
	v_cmp_le_u32_e64 s[28:29], v7, v9
	v_lshlrev_b32_e32 v10, 4, v81
	v_lshl_add_u64 v[28:29], s[74:75], 0, v[24:25]
	v_cndmask_b32_e64 v8, 0, 1, s[28:29]
	v_cmp_ge_u32_e64 s[28:29], v7, v9
	v_lshlrev_b32_e32 v36, 7, v9
	v_and_b32_e32 v10, 0x3ff0, v10
	v_cndmask_b32_e64 v7, 0, 1, s[28:29]
	v_cndmask_b32_e32 v7, v7, v8, vcc
	v_and_b32_e32 v7, 1, v7
	v_cmp_eq_u32_e64 s[28:29], 1, v7
	v_or_b32_e32 v7, 18, v13
	v_cmp_le_u32_e64 s[30:31], v7, v9
	v_mov_b32_e32 v11, v25
	s_mov_b32 s77, 0
	v_cndmask_b32_e64 v8, 0, 1, s[30:31]
	v_cmp_ge_u32_e64 s[30:31], v7, v9
	v_mov_b32_e32 v31, v25
	v_mov_b32_e32 v33, v25
	v_cndmask_b32_e64 v7, 0, 1, s[30:31]
	v_cndmask_b32_e32 v7, v7, v8, vcc
	v_and_b32_e32 v7, 1, v7
	v_cmp_eq_u32_e64 s[30:31], 1, v7
	v_or_b32_e32 v7, 19, v13
	v_cmp_le_u32_e64 s[34:35], v7, v9
	v_mov_b32_e32 v35, v25
	v_mov_b32_e32 v37, v25
	v_cndmask_b32_e64 v8, 0, 1, s[34:35]
	v_cmp_ge_u32_e64 s[34:35], v7, v9
	v_mov_b32_e32 v39, v25
	v_mov_b32_e32 v41, v25
	v_cndmask_b32_e64 v7, 0, 1, s[34:35]
	v_cndmask_b32_e32 v7, v7, v8, vcc
	v_and_b32_e32 v7, 1, v7
	v_cmp_eq_u32_e64 s[34:35], 1, v7
	v_bitop3_b32 v7, v15, v16, 2 bitop3:0x36
	v_lshl_or_b32 v42, v7, 4, v17
	v_or_b32_e32 v7, 24, v13
	v_cmp_le_u32_e64 s[36:37], v7, v9
	v_mov_b32_e32 v43, v25
	v_mov_b32_e32 v45, v25
	v_cndmask_b32_e64 v8, 0, 1, s[36:37]
	v_cmp_ge_u32_e64 s[36:37], v7, v9
	v_mov_b32_e32 v47, v25
	v_mov_b32_e32 v49, v25
	v_cndmask_b32_e64 v7, 0, 1, s[36:37]
	v_cndmask_b32_e32 v7, v7, v8, vcc
	v_and_b32_e32 v7, 1, v7
	v_cmp_eq_u32_e64 s[36:37], 1, v7
	v_or_b32_e32 v7, 25, v13
	v_cmp_le_u32_e64 s[38:39], v7, v9
	v_mov_b32_e32 v51, v25
	v_mov_b32_e32 v53, v25
	v_cndmask_b32_e64 v8, 0, 1, s[38:39]
	v_cmp_ge_u32_e64 s[38:39], v7, v9
	v_mov_b32_e32 v55, v25
	v_lshl_add_u64 v[72:73], s[78:79], 0, v[10:11]
	v_cndmask_b32_e64 v7, 0, 1, s[38:39]
	v_cndmask_b32_e32 v7, v7, v8, vcc
	v_and_b32_e32 v7, 1, v7
	v_cmp_eq_u32_e64 s[38:39], 1, v7
	v_or_b32_e32 v7, 26, v13
	v_cmp_le_u32_e64 s[40:41], v7, v9
	s_mov_b32 s96, 0xbfb8aa3b
	s_mov_b32 s97, 0xa000
	v_cndmask_b32_e64 v8, 0, 1, s[40:41]
	v_cmp_ge_u32_e64 s[40:41], v7, v9
	v_add_u32_e32 v205, v79, v83
	v_mov_b32_e32 v212, 0xa000
	v_cndmask_b32_e64 v7, 0, 1, s[40:41]
	v_cndmask_b32_e32 v7, v7, v8, vcc
	v_and_b32_e32 v7, 1, v7
	v_cmp_eq_u32_e64 s[40:41], 1, v7
	v_or_b32_e32 v7, 27, v13
	v_cmp_le_u32_e64 s[42:43], v7, v9
	s_mov_b32 s84, s33
	s_nop 0
	v_cndmask_b32_e64 v8, 0, 1, s[42:43]
	v_cmp_ge_u32_e64 s[42:43], v7, v9
	v_mov_b32_e32 v9, v25
	s_nop 0
	v_cndmask_b32_e64 v7, 0, 1, s[42:43]
	v_cndmask_b32_e32 v7, v7, v8, vcc
	v_and_b32_e32 v7, 1, v7
	v_cmp_eq_u32_e64 s[42:43], 1, v7
; #define LAS __attribute__((address_space(3)))
; #define PP_FETCH(task_) do { const int c_ = (task_) >> 2, h_ = (task_) & 3; const size_t t0_ = (size_t)c_ * 64; \
;         n_lr = *(const f32x4*)(LR + t0_ * 32 + tid * 4); \
;         _Pragma("unroll") for (int r_ = 0; r_ < 8; ++r_) { const bf16_t* rp_ = PG + (t0_ + rg * 8 + r_) * 2048 + h_ * 128 + c0; n_q[r_] = *(const unsigned*)rp_; n_k[r_] = *(const unsigned*)(rp_ + 512); } } while (0)
; DI void phase_gla_prep(const Params& P, int l, int bid, int nb, LAS unsigned char* lds) {
;     ...
;     if (bid < 2560) PP_FETCH(bid);
;     f32x2 bbs[2] = {{0.f, 0.f}, {0.f, 0.f}};
;     for (int task = bid; task < 2560; task += nb) {
;         const int c = task >> 2, h = task & 3;
;         __syncthreads();
;         if (h != hcur) { hcur = h;
;             for (int e = tid; e < 2 * 16 * 128; e += NTHR) { const int dir = e >> 11, k = (e >> 7) & 15, cc = e & 127;
;                 ((LAS float*)(lds + PP_W))[e] = (dir ? P.w_gk_b : P.w_gk_f)[(size_t)l * 16 * 512 + k * 512 + h * 128 + cc]; }
;             bbs[0] = *(const f32x2*)(P.b_gk_f + l * 512 + h * 128 + c0); bbs[1] = *(const f32x2*)(P.b_gk_b + l * 512 + h * 128 + c0); }
;         *(LAS f32x4*)(lds + PP_LR + tid * 16) = n_lr;
	v_bitop3_b32 v7, v15, v16, 3 bitop3:0x36
	v_lshl_or_b32 v44, v7, 4, v17
	v_lshrrev_b32_e32 v7, 10, v76
	v_lshl_add_u32 v80, v7, 14, 0
	v_mul_u32_u24_e32 v46, 0xa00, v7
	v_lshrrev_b32_e32 v7, 10, v81
	v_lshl_add_u32 v82, v7, 14, 0
	v_mul_u32_u24_e32 v48, 0xa00, v7
	v_bitop3_b32 v7, v65, v12, 7 bitop3:0x6c
	v_lshlrev_b32_e32 v50, 4, v7
	v_lshrrev_b32_e32 v7, 8, v76
	v_lshlrev_b32_e32 v84, 12, v7
	v_bitop3_b32 v7, v7, v65, 7 bitop3:0x78
	v_lshlrev_b32_e32 v52, 4, v7
	v_or_b32_e32 v7, 4, v12
	v_lshlrev_b32_e32 v85, 12, v7
	v_bitop3_b32 v7, v12, v16, 4 bitop3:0x36
	v_lshl_add_u64 v[12:13], s[80:81], 0, v[24:25]
	s_ashr_i32 s80, s33, 2
	s_ashr_i32 s81, s80, 31
	s_lshl_b64 s[82:83], s[80:81], 18
	v_lshl_add_u64 v[12:13], v[12:13], 0, s[82:83]
	v_lshl_add_u64 v[12:13], v[12:13], 0, v[56:57]
	s_lshl_b64 s[80:81], s[80:81], 13
	v_add_co_u32_e32 v14, vcc, s76, v12
	s_add_u32 s44, s44, s80
	s_nop 0
	v_addc_co_u32_e32 v15, vcc, 0, v13, vcc
	s_movk_i32 s76, 0x2000
	s_addc_u32 s45, s45, s81
	v_add_co_u32_e32 v16, vcc, s76, v12
	v_lshlrev_b32_e32 v54, 4, v7
	s_nop 0
	v_addc_co_u32_e32 v17, vcc, 0, v13, vcc
	global_load_dwordx4 v[18:21], v22, s[44:45]
	global_load_dword v174, v[16:17], off offset:-4096
	global_load_dword v176, v[16:17], off
	global_load_dword v177, v[16:17], off offset:1024
	s_movk_i32 s44, 0x3000
	v_add_co_u32_e32 v16, vcc, s44, v12
	s_movk_i32 s44, 0x4000
	s_nop 0
	v_addc_co_u32_e32 v17, vcc, 0, v13, vcc
	v_add_co_u32_e32 v58, vcc, s44, v12
	s_movk_i32 s44, 0x5000
	s_nop 0
	v_addc_co_u32_e32 v59, vcc, 0, v13, vcc
	v_add_co_u32_e32 v60, vcc, s44, v12
	s_movk_i32 s44, 0x6000
	s_nop 0
	v_addc_co_u32_e32 v61, vcc, 0, v13, vcc
	v_add_co_u32_e32 v62, vcc, s44, v12
	s_movk_i32 s44, 0x7000
	s_nop 0
	v_addc_co_u32_e32 v63, vcc, 0, v13, vcc
	global_load_dword v185, v[58:59], off offset:-4096
	global_load_dword v186, v[58:59], off
	global_load_dword v187, v[58:59], off offset:1024
	global_load_dword v193, v[62:63], off offset:-4096
	global_load_dword v199, v[62:63], off
	global_load_dword v200, v[62:63], off offset:1024
	v_add_co_u32_e32 v58, vcc, s44, v12
	v_lshrrev_b32_e32 v7, 8, v81
	s_nop 0
	v_addc_co_u32_e32 v59, vcc, 0, v13, vcc
	global_load_dword v178, v[12:13], off
	global_load_dword v179, v[12:13], off offset:1024
	global_load_dword v192, v[14:15], off offset:1024
	global_load_dword v196, v[16:17], off offset:1024
	global_load_dword v209, v[60:61], off offset:1024
	global_load_dword v213, v[58:59], off
	global_load_dword v214, v[58:59], off offset:1024
	v_lshlrev_b32_e32 v12, 12, v7
	v_bitop3_b32 v7, v7, v65, 7 bitop3:0x78
	v_lshlrev_b32_e32 v58, 4, v7
	v_mov_b32_e32 v7, v25
	v_lshl_add_u64 v[60:61], s[54:55], 0, v[6:7]
	v_lshl_add_u64 v[62:63], s[58:59], 0, v[6:7]
	v_lshl_add_u64 v[6:7], s[50:51], 0, v[6:7]
	s_mov_b64 s[44:45], 0x3b670000
	v_lshl_add_u64 v[64:65], v[6:7], 0, s[44:45]
	v_lshl_add_u64 v[6:7], s[50:51], 0, v[22:23]
	s_mov_b64 s[44:45], 0x30270000
	v_lshl_add_u64 v[70:71], v[6:7], 0, s[44:45]
	s_mov_b64 s[44:45], 0x36670000
	v_lshl_add_u64 v[74:75], v[4:5], 0, s[44:45]
	v_lshlrev_b32_e32 v4, 2, v76
	s_movk_i32 s76, 0x1e00
	v_and_or_b32 v181, v4, s76, v78
	v_add_u32_e32 v182, s70, v4
	v_or_b32_e32 v4, 0x1000, v3
	v_and_or_b32 v183, v4, s76, v78
	v_add_u32_e32 v184, s70, v4
	v_mov_b32_e32 v4, s57
	v_mov_b32_e32 v5, s53
	v_cmp_gt_u32_e32 vcc, s71, v136
	v_lshlrev_b32_e32 v8, 4, v76
	s_movk_i32 s44, 0xe00
	v_cndmask_b32_e32 v77, v4, v5, vcc
	v_mov_b32_e32 v4, s56
	v_mov_b32_e32 v5, s52
	v_cndmask_b32_e32 v76, v4, v5, vcc
	v_lshlrev_b32_e32 v4, 2, v81
	v_and_or_b32 v188, v4, s76, v78
	v_add_u32_e32 v189, s70, v4
	v_add_u32_e32 v4, 0x2800, v3
	v_and_or_b32 v190, v4, s76, v78
	v_add_u32_e32 v191, s70, v4
	v_or_b32_e32 v4, 0xc00, v136
	v_and_or_b32 v23, v3, s44, v78
	v_lshlrev_b32_e32 v5, 2, v4
	v_add_u32_e32 v3, 0x3800, v3
	v_and_or_b32 v194, v5, s76, v78
	v_and_or_b32 v197, v3, s76, v78
	v_lshlrev_b32_e32 v78, 1, v2
	v_mbcnt_lo_u32_b32 v2, -1, 0
	v_and_b32_e32 v8, 0x3ff0, v8
	v_mov_b32_e32 v24, v25
	v_mbcnt_hi_u32_b32 v210, -1, v2
	v_mov_b32_e32 v2, 0x80
	v_mov_b32_e32 v59, v25
	v_lshl_add_u64 v[68:69], s[78:79], 0, v[8:9]
	v_add_u32_e32 v195, s70, v5
	v_cmp_gt_u32_e64 s[44:45], s44, v4
	v_add_u32_e32 v198, s70, v3
	s_mov_b32 s70, -1
	s_mov_b64 s[78:79], 0x800
	s_mov_b64 s[80:81], 0x29e76000
	s_mov_b64 s[82:83], 0x29e74000
	v_add_u32_e32 v201, v80, v8
	v_add_u32_e32 v202, v82, v10
	v_add_u32_e32 v206, v79, v84
	v_add_u32_e32 v207, v79, v85
	v_add_u32_e32 v208, v79, v12
	v_lshl_or_b32 v211, v210, 2, v2
	v_mov_b64_e32 v[82:83], v[24:25]
	v_mov_b64_e32 v[80:81], v[24:25]
	s_waitcnt vmcnt(0)
	s_branch .LBB0_336

; #define LAS __attribute__((address_space(3)))
; DI void phase_gla_prep(const Params& P, int l, int bid, int nb, LAS unsigned char* lds) {
;     ...
;     for (int task = bid; task < 2560; task += nb) {
;         const int c = task >> 2, h = task & 3;
;         __syncthreads();
;         if (h != hcur) { hcur = h;
;             for (int e = tid; e < 2 * 16 * 128; e += NTHR) { const int dir = e >> 11, k = (e >> 7) & 15, cc = e & 127;
;                 ((LAS float*)(lds + PP_W))[e] = (dir ? P.w_gk_b : P.w_gk_f)[(size_t)l * 16 * 512 + k * 512 + h * 128 + cc]; }
;             bbs[0] = *(const f32x2*)(P.b_gk_f + l * 512 + h * 128 + c0); bbs[1] = *(const f32x2*)(P.b_gk_b + l * 512 + h * 128 + c0); }
.LBB0_336:
	s_and_b32 s71, s84, 3
	s_cmp_eq_u32 s71, s70
	s_waitcnt vmcnt(16) lgkmcnt(0)
	s_barrier
	s_cbranch_scc1 .LBB0_340
	s_lshl_b32 s70, s71, 7
	v_or_b32_e32 v2, s70, v23
	v_lshlrev_b32_e32 v4, 2, v2
	v_or_b32_e32 v2, s70, v181
	v_lshlrev_b32_e32 v2, 2, v2
	v_or_b32_e32 v3, s70, v183
	v_lshlrev_b32_e32 v3, 2, v3
	global_load_dword v5, v2, s[52:53]
	global_load_dword v6, v3, s[52:53]
	v_or_b32_e32 v2, s70, v188
	v_lshlrev_b32_e32 v24, 2, v2
	v_lshl_add_u64 v[2:3], v[76:77], 0, v[24:25]
	global_load_dword v2, v[2:3], off
	s_nop 0
	global_load_dword v3, v4, s[52:53]
	s_nop 0
	global_load_dword v4, v4, s[56:57]
	v_or_b32_e32 v7, s70, v190
	v_lshlrev_b32_e32 v7, 2, v7
	global_load_dword v7, v7, s[56:57]
	v_or_b32_e32 v8, s70, v194
	v_lshlrev_b32_e32 v8, 2, v8
	global_load_dword v8, v8, s[56:57]
	s_waitcnt vmcnt(6)
	ds_write_b32 v182, v5
	s_waitcnt vmcnt(5)
	ds_write_b32 v184, v6
	s_waitcnt vmcnt(2)
	ds_write2st64_b32 v180, v3, v4 offset1:32
	s_waitcnt vmcnt(1)
	ds_write_b32 v191, v7
	ds_write_b32 v189, v2
	s_waitcnt vmcnt(0)
	ds_write_b32 v195, v8
	s_and_saveexec_b64 s[86:87], s[44:45]
	s_cbranch_execz .LBB0_339
	v_or_b32_e32 v2, s70, v197
	v_lshlrev_b32_e32 v2, 2, v2
	global_load_dword v2, v2, s[56:57]
	s_waitcnt vmcnt(0)
	ds_write_b32 v198, v2

; #define LAS __attribute__((address_space(3)))
; DI float logsigmoid_fast(float z) { return fminf(z, 0.f) - 0.6931471805599453f * __builtin_amdgcn_logf(1.0f + __builtin_amdgcn_exp2f(-fabsf(z) * LOG2E)); }
; DI void phase_gla_prep(const Params& P, int l, int bid, int nb, LAS unsigned char* lds) {
;     ...
;         asm volatile("s_waitcnt lgkmcnt(0)" ::: "memory"); __builtin_amdgcn_s_barrier(); asm volatile("" ::: "memory");
; #pragma unroll 1
;         for (int dir = 0; dir < 2; ++dir) {
;             float w0[16], w1[16];
; #pragma unroll
;             for (int k = 0; k < 16; ++k) { const f32x2 t = *(const LAS f32x2*)(lds + PP_W + ((dir * 16 + k) * 128 + c0) * 4); w0[k] = t.x; w1[k] = t.y; }
;             const f32x2 bb = dir ? bbs[1] : bbs[0];
;             float g0[8], g1[8];
; #pragma unroll
;             for (int r = 0; r < 8; ++r) { float z0 = bb.x, z1 = bb.y; const LAS float* lr = (const LAS float*)(lds + PP_LR) + (rg * 8 + r) * 32 + dir * 16;
; #pragma unroll
;                 for (int k4 = 0; k4 < 4; ++k4) { const f32x4 t = *(const LAS f32x4*)(lr + k4 * 4);
; #pragma unroll
;                     for (int u = 0; u < 4; ++u) { z0 += t[u] * w0[k4 * 4 + u]; z1 += t[u] * w1[k4 * 4 + u]; } }
;                 g0[r] = logsigmoid_fast(z0) * 0.0625f; g1[r] = logsigmoid_fast(z1) * 0.0625f; __builtin_amdgcn_sched_barrier(0); }
;             float tot0, tot1;
;             if (dir == 0) {
; #pragma unroll
;                 for (int r = 1; r < 8; ++r) { g0[r] += g0[r - 1]; g1[r] += g1[r - 1]; }
;                 float s0 = g0[7], s1 = g1[7];
; #pragma unroll
;                 for (int o = 8; o < 64; o <<= 1) { const float t0 = __shfl_up(s0, o), t1 = __shfl_up(s1, o); if (lane >= o) { s0 += t0; s1 += t1; } }
;                 const float e0 = s0 - g0[7], e1 = s1 - g1[7];
; #pragma unroll
;                 for (int r = 0; r < 8; ++r) { g0[r] += e0; g1[r] += e1; }
;                 tot0 = __shfl(s0, 56 + dpl); tot1 = __shfl(s1, 56 + dpl);
;             } else {
; #pragma unroll
;                 for (int r = 6; r >= 0; --r) { g0[r] += g0[r + 1]; g1[r] += g1[r + 1]; }
;                 float s0 = g0[0], s1 = g1[0];
; #pragma unroll
;                 for (int o = 8; o < 64; o <<= 1) { const float t0 = __shfl_down(s0, o), t1 = __shfl_down(s1, o); if (lane + o < 64) { s0 += t0; s1 += t1; } }
.LBB0_342:
	v_lshlrev_b32_e32 v114, 16, v2
	v_and_b32_e32 v115, 0xffff0000, v2
	v_and_b32_e32 v2, 63, v210
	v_cmp_gt_u32_e32 vcc, 56, v2
	v_lshlrev_b32_e32 v112, 16, v3
	v_and_b32_e32 v113, 0xffff0000, v3
	v_cndmask_b32_e64 v3, 0, 8, vcc
	v_cmp_gt_u32_e32 vcc, 48, v2
	v_add_lshl_u32 v79, v3, v210, 2
	s_waitcnt lgkmcnt(0)
	s_barrier
	v_cndmask_b32_e64 v2, 0, 16, vcc
	v_add_lshl_u32 v215, v2, v210, 2
	v_and_b32_e32 v2, 64, v210
	v_or_b32_e32 v3, v2, v138
	v_lshlrev_b32_e32 v216, 2, v3
	v_add_u32_e32 v3, -8, v210
	v_cmp_lt_i32_e32 vcc, v3, v2
	s_ashr_i32 s85, s84, 31
	v_lshlrev_b32_e32 v84, 16, v16
	v_cndmask_b32_e32 v3, v3, v210, vcc
	v_lshlrev_b32_e32 v217, 2, v3
	v_add_u32_e32 v3, -16, v210
	v_cmp_lt_i32_e32 vcc, v3, v2
	v_and_b32_e32 v85, 0xffff0000, v16
	v_lshlrev_b32_e32 v86, 16, v14
	v_cndmask_b32_e32 v3, v3, v210, vcc
	v_lshlrev_b32_e32 v218, 2, v3
	v_subrev_u32_e32 v3, 32, v210
	v_cmp_lt_i32_e32 vcc, v3, v2
	v_and_b32_e32 v87, 0xffff0000, v14
	v_lshlrev_b32_e32 v88, 16, v17
	v_cndmask_b32_e32 v2, v3, v210, vcc
	v_and_b32_e32 v89, 0xffff0000, v17
	v_lshlrev_b32_e32 v90, 16, v15
	v_and_b32_e32 v91, 0xffff0000, v15
	v_lshlrev_b32_e32 v92, 16, v13
	v_and_b32_e32 v93, 0xffff0000, v13
	v_lshlrev_b32_e32 v94, 16, v11
	v_and_b32_e32 v95, 0xffff0000, v11
	v_lshlrev_b32_e32 v96, 16, v9
	v_and_b32_e32 v97, 0xffff0000, v9
	v_lshlrev_b32_e32 v98, 16, v12
	v_and_b32_e32 v99, 0xffff0000, v12
	v_lshlrev_b32_e32 v100, 16, v10
	v_and_b32_e32 v101, 0xffff0000, v10
	v_lshlrev_b32_e32 v102, 16, v7
	v_and_b32_e32 v103, 0xffff0000, v7
	v_lshlrev_b32_e32 v104, 16, v5
	v_and_b32_e32 v105, 0xffff0000, v5
	v_lshlrev_b32_e32 v106, 16, v8
	v_and_b32_e32 v107, 0xffff0000, v8
	v_lshlrev_b32_e32 v108, 16, v6
	v_and_b32_e32 v109, 0xffff0000, v6
	v_lshlrev_b32_e32 v110, 16, v4
	v_and_b32_e32 v111, 0xffff0000, v4
	s_mov_b32 s76, 0
	v_lshlrev_b32_e32 v219, 2, v2
	v_or_b32_e32 v220, 0xe0, v216
	s_mov_b64 s[88:89], -1
	s_cmp_lg_u32 s86, 0
	s_cbranch_scc1 .Lgp_full_0
	s_waitcnt vmcnt(17)
	s_branch .LBB0_344
.Lgp_full_0:
	s_waitcnt vmcnt(0)
	s_branch .LBB0_344

; #define LAS __attribute__((address_space(3)))
; DI void phase_gla_prep(const Params& P, int l, int bid, int nb, LAS unsigned char* lds) {
;     const int tid = threadIdx.x, wid = tid >> 6, lane = tid & 63, dpl = lane & 7, rg = lane >> 3, r32 = lane & 31, hi = lane >> 5;
;     const bf16_t* PG = (const bf16_t*)(P.ws + WS_PG); const float* LR = (const float*)(P.ws + WS_LR);
;     const int c0 = wid * 16 + dpl * 2;
;     const int p0 = (c0 & ~15) | (c0 & 3) | ((c0 & 4) << 1) | ((c0 & 8) >> 1);
;     ...
;         { const int dir = wid >> 2, ti = (wid >> 1) & 1, tj = wid & 1; const int i = ti * 32 + r32, jr = tj * 32 + r32;
;           f32x16 acc; for (int x = 0; x < 16; ++x) acc[x] = 0.f;
; #pragma unroll
;           for (int s = 0; s < 8; ++s) { const int ch = 2 * s + hi;
;               const bf16x8 a = *(const LAS bf16x8*)(lds + PP_KD + dir * 16384 + jr * 256 + ((ch ^ (jr & 15)) << 4));
;               const bf16x8 b = *(const LAS bf16x8*)(lds + PP_QD + dir * 16384 + i * 256 + ((ch ^ (i & 15)) << 4));
;               acc = __builtin_amdgcn_mfma_f32_32x32x16_bf16(a, b, acc, 0, 0, 0); }
;           unsigned char* am = P.ws + GL_PD + ((size_t)dir * 2560 + task) * GL_PD_BYTES + 16384;
; #pragma unroll
;           for (int a4 = 0; a4 < 4; ++a4) { float v[4];
; #pragma unroll
;               for (int b4 = 0; b4 < 4; ++b4) { const int j = tj * 32 + 8 * a4 + 4 * hi + b4; const bool keep = dir ? (j >= i) : (j <= i); v[b4] = keep ? acc[a4 * 4 + b4] : 0.f; }
.LBB0_894:
	s_cmp_lt_i32 s72, 9
	s_cselect_b64 s[0:1], -1, 0
	s_cmp_gt_i32 s73, 8
	s_cselect_b64 s[2:3], -1, 0
	s_and_b64 s[0:1], s[0:1], s[2:3]
	s_andn2_b64 vcc, exec, s[0:1]
	s_cbranch_vccnz .LBB0_962
	s_cmpk_gt_i32 s33, 0x9ff
	v_and_b32_e32 v136, 0x3ff, v0
	s_cbranch_scc1 .LBB0_912
	v_lshrrev_b32_e32 v137, 6, v136
	v_and_b32_e32 v138, 7, v136
	v_lshlrev_b32_e32 v3, 2, v136
	v_lshlrev_b32_e32 v2, 4, v137
	v_and_or_b32 v4, v3, 8, v2
	v_lshlrev_b32_e32 v5, 1, v138
	v_and_b32_e32 v6, 4, v136
	v_bfe_u32 v9, v136, 3, 3
	v_and_or_b32 v6, v5, 2, v6
	v_lshrrev_b32_e32 v10, 3, v4
	v_bitop3_b32 v4, v9, v136, 7 bitop3:0x78
	s_add_u32 s74, s50, 0x10440000
	v_or_b32_e32 v8, v2, v5
	v_and_b32_e32 v5, 31, v136
	v_lshlrev_b32_e32 v11, 1, v6
	v_lshlrev_b32_e32 v32, 4, v4
	v_bfe_u32 v4, v136, 6, 1
	v_lshrrev_b32_e32 v6, 2, v136
	s_addc_u32 s75, s51, 0
	v_and_or_b32 v9, v6, 32, v5
	v_lshlrev_b32_e32 v6, 5, v4
	s_add_u32 s44, s50, 0x1f440000
	v_lshlrev_b32_e32 v2, 3, v5
	v_lshrrev_b32_e32 v12, 8, v136
	v_or_b32_e32 v5, v6, v5
	s_addc_u32 s45, s51, 0
	v_lshlrev_b32_e32 v13, 14, v12
	s_add_i32 s2, 0, 0x12000
	v_lshlrev_b32_e32 v5, 8, v5
	v_bfe_u32 v139, v136, 5, 1
	v_add3_u32 v140, s2, v13, v5
	v_lshlrev_b32_e32 v5, 8, v9
	v_add3_u32 v141, 0, v13, v5
	v_lshl_or_b32 v13, v139, 2, v6
	v_lshlrev_b32_e32 v6, 2, v8
	s_add_i32 s2, 0, 0x1a200
	v_add_u32_e32 v143, s2, v6
	s_add_i32 s2, 0, 0x1a400
	v_add_u32_e32 v144, s2, v6
	s_add_i32 s2, 0, 0x1a600
	v_add_u32_e32 v145, s2, v6
	s_add_i32 s2, 0, 0x1a800
	v_add_u32_e32 v147, s2, v6
	s_add_i32 s2, 0, 0x1aa00
	v_add_u32_e32 v148, s2, v6
	s_add_i32 s2, 0, 0x1ac00
	v_add_u32_e32 v149, s2, v6
	s_add_i32 s2, 0, 0x1ae00
	v_add_u32_e32 v150, s2, v6
	s_add_i32 s2, 0, 0x1b000
	v_add_u32_e32 v151, s2, v6
	s_add_i32 s2, 0, 0x1b200
	v_add_u32_e32 v152, s2, v6
	s_add_i32 s2, 0, 0x1b400
	v_add_u32_e32 v153, s2, v6
	s_add_i32 s2, 0, 0x1b600
	v_add_u32_e32 v154, s2, v6
	s_add_i32 s2, 0, 0x1b800
	v_add_u32_e32 v155, s2, v6
	s_add_i32 s2, 0, 0x1ba00
	v_add_u32_e32 v156, s2, v6
	s_add_i32 s2, 0, 0x1bc00
	s_waitcnt lgkmcnt(0)
	v_and_b32_e32 v7, 63, v136
	v_and_b32_e32 v64, 56, v136
	v_add_u32_e32 v157, s2, v6
	s_add_i32 s2, 0, 0x1be00
	v_lshlrev_b32_e32 v24, 1, v8
	v_lshlrev_b32_e32 v30, 7, v8
	v_cmp_gt_u32_e64 s[0:1], 8, v7
	v_add_u32_e32 v158, s2, v6
	v_cmp_gt_u32_e64 s[2:3], 56, v7
	v_cmp_gt_u32_e64 s[4:5], 48, v7
	v_cmp_gt_u32_e64 s[6:7], 32, v7
	v_cmp_gt_u32_e64 s[8:9], 16, v7
	v_bitop3_b32 v7, v10, v136, 8 bitop3:0x78
	v_lshl_or_b32 v8, v64, 8, v11
	v_lshl_add_u32 v159, v7, 4, v8
	v_or_b32_e32 v7, 1, v64
	v_bitop3_b32 v8, v10, v7, 9 bitop3:0x78
	v_lshl_or_b32 v7, v7, 8, v11
	v_lshl_add_u32 v160, v8, 4, v7
	v_or_b32_e32 v7, 2, v64
	v_bitop3_b32 v8, v10, v7, 10 bitop3:0x78
	v_lshl_or_b32 v7, v7, 8, v11
	v_lshl_add_u32 v162, v8, 4, v7
	v_or_b32_e32 v7, 3, v64
	v_bitop3_b32 v8, v10, v7, 11 bitop3:0x78
	v_lshl_or_b32 v7, v7, 8, v11
	v_lshl_add_u32 v164, v8, 4, v7
	v_or_b32_e32 v7, 4, v64
	v_bitop3_b32 v8, v10, v7, 12 bitop3:0x78
	v_lshl_or_b32 v7, v7, 8, v11
	v_lshl_add_u32 v165, v8, 4, v7
	v_or_b32_e32 v7, 5, v64
	v_bitop3_b32 v8, v10, v7, 13 bitop3:0x78
	v_lshl_or_b32 v7, v7, 8, v11
	v_lshl_add_u32 v166, v8, 4, v7
	v_or_b32_e32 v7, 6, v64
	v_bitop3_b32 v8, v10, v7, 14 bitop3:0x78
	v_lshl_or_b32 v7, v7, 8, v11
	v_lshl_add_u32 v167, v8, 4, v7
	v_or_b32_e32 v7, 7, v64
	v_bitop3_b32 v8, v10, v7, 15 bitop3:0x78
	v_lshl_or_b32 v7, v7, 8, v11
	v_and_b32_e32 v14, 15, v136
	v_lshl_add_u32 v168, v8, 4, v7
	v_bitop3_b32 v7, v139, v136, 15 bitop3:0x78
	v_lshlrev_b32_e32 v169, 4, v7
	v_bitop3_b32 v7, v139, v14, 2 bitop3:0x36
	v_lshlrev_b32_e32 v170, 4, v7
	v_bitop3_b32 v7, v139, v14, 4 bitop3:0x36
	v_lshlrev_b32_e32 v171, 4, v7
	v_bitop3_b32 v7, v139, v14, 6 bitop3:0x36
	v_lshlrev_b32_e32 v172, 4, v7
	v_bitop3_b32 v7, v139, v14, 8 bitop3:0x36
	v_lshlrev_b32_e32 v173, 4, v7
	v_bitop3_b32 v7, v139, v14, 10 bitop3:0x36
	v_lshlrev_b32_e32 v174, 4, v7
	v_bitop3_b32 v7, v139, v14, 12 bitop3:0x36
	v_lshlrev_b32_e32 v175, 4, v7
	v_bitop3_b32 v7, v139, v14, 14 bitop3:0x36
	v_cmp_le_u32_e32 vcc, v13, v9
	s_movk_i32 s10, 0x100
	v_lshlrev_b32_e32 v176, 4, v7
	v_cndmask_b32_e64 v7, 0, 1, vcc
	v_cmp_ge_u32_e32 vcc, v13, v9
	v_cmp_lt_u32_e64 s[12:13], v13, v9
	v_lshlrev_b32_e32 v15, 2, v4
	v_cndmask_b32_e64 v8, 0, 1, vcc
	v_cmp_gt_u32_e32 vcc, s10, v136
	v_lshrrev_b32_e32 v65, 1, v136
	v_lshlrev_b32_e32 v17, 3, v139
	v_cndmask_b32_e32 v7, v8, v7, vcc
	v_and_b32_e32 v7, 1, v7
	v_cmp_eq_u32_e64 s[10:11], 1, v7
	v_or_b32_e32 v7, 1, v13
	v_cndmask_b32_e64 v8, 0, 1, s[12:13]
	v_cmp_ge_u32_e64 s[12:13], v7, v9
	v_bfe_u32 v16, v136, 1, 3
	v_add_u32_e32 v76, 0x200, v136
	v_cndmask_b32_e64 v7, 0, 1, s[12:13]
	v_cndmask_b32_e32 v7, v7, v8, vcc
	v_and_b32_e32 v7, 1, v7
	v_cmp_eq_u32_e64 s[12:13], 1, v7
	v_or_b32_e32 v7, 2, v13
	v_cmp_le_u32_e64 s[14:15], v7, v9
	s_add_i32 s70, 0, 0x1a000
	v_add_u32_e32 v81, 0x600, v136
	v_cndmask_b32_e64 v8, 0, 1, s[14:15]
	v_cmp_ge_u32_e64 s[14:15], v7, v9
	s_add_u32 s78, s50, 0x29e70000
	s_addc_u32 s79, s51, 0
	v_cndmask_b32_e64 v7, 0, 1, s[14:15]
	v_cndmask_b32_e32 v7, v7, v8, vcc
	v_and_b32_e32 v7, 1, v7
	v_cmp_eq_u32_e64 s[14:15], 1, v7
	v_or_b32_e32 v7, 3, v13
	v_cmp_le_u32_e64 s[16:17], v7, v9
	s_lshl_b32 s65, s33, 8
	s_and_b32 s65, s65, 0x300
	v_cndmask_b32_e64 v8, 0, 1, s[16:17]
	v_cmp_ge_u32_e64 s[16:17], v7, v9
	s_add_u32 s80, s74, s65
	v_mov_b32_e32 v25, 0
	v_cndmask_b32_e64 v7, 0, 1, s[16:17]
	v_cndmask_b32_e32 v7, v7, v8, vcc
	v_and_b32_e32 v7, 1, v7
	v_cmp_eq_u32_e64 s[16:17], 1, v7
	v_bitop3_b32 v7, v15, v65, 7 bitop3:0x78
	v_lshl_or_b32 v38, v7, 4, v17
	v_or_b32_e32 v7, 8, v13
	v_cmp_le_u32_e64 s[18:19], v7, v9
; #define LAS __attribute__((address_space(3)))
; DI void phase_gla_prep(const Params& P, int l, int bid, int nb, LAS unsigned char* lds) {
;     ...
;         { const int dir = wid >> 2, ti = (wid >> 1) & 1, tj = wid & 1; const int i = ti * 32 + r32, jr = tj * 32 + r32;
;           f32x16 acc; for (int x = 0; x < 16; ++x) acc[x] = 0.f;
; #pragma unroll
;           for (int s = 0; s < 8; ++s) { const int ch = 2 * s + hi;
;               const bf16x8 a = *(const LAS bf16x8*)(lds + PP_KD + dir * 16384 + jr * 256 + ((ch ^ (jr & 15)) << 4));
;               const bf16x8 b = *(const LAS bf16x8*)(lds + PP_QD + dir * 16384 + i * 256 + ((ch ^ (i & 15)) << 4));
;               acc = __builtin_amdgcn_mfma_f32_32x32x16_bf16(a, b, acc, 0, 0, 0); }
;           unsigned char* am = P.ws + GL_PD + ((size_t)dir * 2560 + task) * GL_PD_BYTES + 16384;
; #pragma unroll
;           for (int a4 = 0; a4 < 4; ++a4) { float v[4];
; #pragma unroll
;               for (int b4 = 0; b4 < 4; ++b4) { const int j = tj * 32 + 8 * a4 + 4 * hi + b4; const bool keep = dir ? (j >= i) : (j <= i); v[b4] = keep ? acc[a4 * 4 + b4] : 0.f; }
	s_addc_u32 s81, s75, 0
	v_mul_u32_u24_e32 v34, 0xa00, v12
	v_cndmask_b32_e64 v8, 0, 1, s[18:19]
	v_cmp_ge_u32_e64 s[18:19], v7, v9
	v_lshlrev_b32_e32 v83, 12, v12
	v_lshlrev_b32_e32 v56, 12, v64
	v_cndmask_b32_e64 v7, 0, 1, s[18:19]
	v_cndmask_b32_e32 v7, v7, v8, vcc
	v_and_b32_e32 v7, 1, v7
	v_cmp_eq_u32_e64 s[18:19], 1, v7
	v_or_b32_e32 v7, 9, v13
	v_cmp_le_u32_e64 s[20:21], v7, v9
	v_mov_b32_e32 v57, v25
	s_movk_i32 s65, 0x1000
	v_cndmask_b32_e64 v8, 0, 1, s[20:21]
	v_cmp_ge_u32_e64 s[20:21], v7, v9
	v_lshlrev_b32_e32 v22, 4, v136
	v_mov_b32_e32 v23, v25
	v_cndmask_b32_e64 v7, 0, 1, s[20:21]
	v_cndmask_b32_e32 v7, v7, v8, vcc
	v_and_b32_e32 v7, 1, v7
	v_cmp_eq_u32_e64 s[20:21], 1, v7
	v_or_b32_e32 v7, 10, v13
	v_cmp_le_u32_e64 s[22:23], v7, v9
	v_lshl_add_u64 v[26:27], s[44:45], 0, v[22:23]
	v_and_b32_e32 v4, 0xff, v136
	v_cndmask_b32_e64 v8, 0, 1, s[22:23]
	v_cmp_ge_u32_e64 s[22:23], v7, v9
	v_add_u32_e32 v142, s70, v6
	v_lshl_add_u32 v79, v4, 1, 0
	v_cndmask_b32_e64 v7, 0, 1, s[22:23]
	v_cndmask_b32_e32 v7, v7, v8, vcc
	v_and_b32_e32 v7, 1, v7
	v_cmp_eq_u32_e64 s[22:23], 1, v7
	v_or_b32_e32 v7, 11, v13
	v_cmp_le_u32_e64 s[24:25], v7, v9
	v_lshlrev_b32_e32 v4, 7, v4
	v_mov_b32_e32 v5, v25
	v_cndmask_b32_e64 v8, 0, 1, s[24:25]
	v_cmp_ge_u32_e64 s[24:25], v7, v9
	v_lshl_add_u32 v178, v64, 7, 0
	v_lshl_add_u64 v[4:5], s[50:51], 0, v[4:5]
	v_cndmask_b32_e64 v7, 0, 1, s[24:25]
	v_cndmask_b32_e32 v7, v7, v8, vcc
	v_and_b32_e32 v7, 1, v7
	v_cmp_eq_u32_e64 s[24:25], 1, v7
	v_bitop3_b32 v7, v15, v16, 1 bitop3:0x36
	v_lshl_or_b32 v40, v7, 4, v17
	v_or_b32_e32 v7, 16, v13
	v_cmp_le_u32_e64 s[26:27], v7, v9
	v_and_b32_e32 v78, 0x7f, v136
	s_movk_i32 s64, 0x200
	v_cndmask_b32_e64 v8, 0, 1, s[26:27]
	v_cmp_ge_u32_e64 s[26:27], v7, v9
	v_lshl_add_u64 v[66:67], s[78:79], 0, v[22:23]
	v_add_u32_e32 v183, s70, v3
	v_cndmask_b32_e64 v7, 0, 1, s[26:27]
	v_cndmask_b32_e32 v7, v7, v8, vcc
	v_and_b32_e32 v7, 1, v7
	v_cmp_eq_u32_e64 s[26:27], 1, v7
	v_or_b32_e32 v7, 17, v13
	v_cmp_le_u32_e64 s[28:29], v7, v9
	v_lshlrev_b32_e32 v10, 4, v81
	v_lshl_add_u64 v[28:29], s[74:75], 0, v[24:25]
	v_cndmask_b32_e64 v8, 0, 1, s[28:29]
	v_cmp_ge_u32_e64 s[28:29], v7, v9
	v_lshlrev_b32_e32 v36, 7, v9
	v_and_b32_e32 v10, 0x3ff0, v10
	v_cndmask_b32_e64 v7, 0, 1, s[28:29]
	v_cndmask_b32_e32 v7, v7, v8, vcc
	v_and_b32_e32 v7, 1, v7
	v_cmp_eq_u32_e64 s[28:29], 1, v7
	v_or_b32_e32 v7, 18, v13
	v_cmp_le_u32_e64 s[30:31], v7, v9
	v_mov_b32_e32 v11, v25
	s_mov_b32 s77, 0
	v_cndmask_b32_e64 v8, 0, 1, s[30:31]
	v_cmp_ge_u32_e64 s[30:31], v7, v9
	v_mov_b32_e32 v31, v25
	v_mov_b32_e32 v33, v25
	v_cndmask_b32_e64 v7, 0, 1, s[30:31]
	v_cndmask_b32_e32 v7, v7, v8, vcc
	v_and_b32_e32 v7, 1, v7
	v_cmp_eq_u32_e64 s[30:31], 1, v7
	v_or_b32_e32 v7, 19, v13
	v_cmp_le_u32_e64 s[34:35], v7, v9
	v_mov_b32_e32 v35, v25
	v_mov_b32_e32 v37, v25
	v_cndmask_b32_e64 v8, 0, 1, s[34:35]
	v_cmp_ge_u32_e64 s[34:35], v7, v9
	v_mov_b32_e32 v39, v25
	v_mov_b32_e32 v41, v25
	v_cndmask_b32_e64 v7, 0, 1, s[34:35]
	v_cndmask_b32_e32 v7, v7, v8, vcc
	v_and_b32_e32 v7, 1, v7
	v_cmp_eq_u32_e64 s[34:35], 1, v7
	v_bitop3_b32 v7, v15, v16, 2 bitop3:0x36
	v_lshl_or_b32 v42, v7, 4, v17
	v_or_b32_e32 v7, 24, v13
	v_cmp_le_u32_e64 s[36:37], v7, v9
	v_mov_b32_e32 v43, v25
	v_mov_b32_e32 v45, v25
	v_cndmask_b32_e64 v8, 0, 1, s[36:37]
	v_cmp_ge_u32_e64 s[36:37], v7, v9
	v_mov_b32_e32 v47, v25
	v_mov_b32_e32 v49, v25
	v_cndmask_b32_e64 v7, 0, 1, s[36:37]
	v_cndmask_b32_e32 v7, v7, v8, vcc
	v_and_b32_e32 v7, 1, v7
	v_cmp_eq_u32_e64 s[36:37], 1, v7
	v_or_b32_e32 v7, 25, v13
	v_cmp_le_u32_e64 s[38:39], v7, v9
	v_mov_b32_e32 v51, v25
	v_mov_b32_e32 v53, v25
	v_cndmask_b32_e64 v8, 0, 1, s[38:39]
	v_cmp_ge_u32_e64 s[38:39], v7, v9
	v_mov_b32_e32 v55, v25
	v_lshl_add_u64 v[72:73], s[78:79], 0, v[10:11]
	v_cndmask_b32_e64 v7, 0, 1, s[38:39]
	v_cndmask_b32_e32 v7, v7, v8, vcc
	v_and_b32_e32 v7, 1, v7
	v_cmp_eq_u32_e64 s[38:39], 1, v7
	v_or_b32_e32 v7, 26, v13
	v_cmp_le_u32_e64 s[40:41], v7, v9
	s_mov_b32 s90, 0xbfb8aa3b
	s_mov_b32 s91, 0xa000
	v_cndmask_b32_e64 v8, 0, 1, s[40:41]
	v_cmp_ge_u32_e64 s[40:41], v7, v9
	v_add_u32_e32 v208, v79, v83
	v_mov_b32_e32 v215, 0xa000
	v_cndmask_b32_e64 v7, 0, 1, s[40:41]
	v_cndmask_b32_e32 v7, v7, v8, vcc
	v_and_b32_e32 v7, 1, v7
	v_cmp_eq_u32_e64 s[40:41], 1, v7
	v_or_b32_e32 v7, 27, v13
	v_cmp_le_u32_e64 s[42:43], v7, v9
	s_nop 1
	v_cndmask_b32_e64 v8, 0, 1, s[42:43]
	v_cmp_ge_u32_e64 s[42:43], v7, v9
	v_mov_b32_e32 v9, v25
	s_nop 0
	v_cndmask_b32_e64 v7, 0, 1, s[42:43]
	v_cndmask_b32_e32 v7, v7, v8, vcc
	v_and_b32_e32 v7, 1, v7
	v_cmp_eq_u32_e64 s[42:43], 1, v7
; #define LAS __attribute__((address_space(3)))
; #define PP_FETCH(task_) do { const int c_ = (task_) >> 2, h_ = (task_) & 3; const size_t t0_ = (size_t)c_ * 64; \
;         n_lr = *(const f32x4*)(LR + t0_ * 32 + tid * 4); \
;         _Pragma("unroll") for (int r_ = 0; r_ < 8; ++r_) { const bf16_t* rp_ = PG + (t0_ + rg * 8 + r_) * 2048 + h_ * 128 + c0; n_q[r_] = *(const unsigned*)rp_; n_k[r_] = *(const unsigned*)(rp_ + 512); } } while (0)
; DI void phase_gla_prep(const Params& P, int l, int bid, int nb, LAS unsigned char* lds) {
;     ...
;     if (bid < 2560) PP_FETCH(bid);
;     f32x2 bbs[2] = {{0.f, 0.f}, {0.f, 0.f}};
;     for (int task = bid; task < 2560; task += nb) {
;         const int c = task >> 2, h = task & 3;
;         __syncthreads();
;         if (h != hcur) { hcur = h;
;             for (int e = tid; e < 2 * 16 * 128; e += NTHR) { const int dir = e >> 11, k = (e >> 7) & 15, cc = e & 127;
;                 ((LAS float*)(lds + PP_W))[e] = (dir ? P.w_gk_b : P.w_gk_f)[(size_t)l * 16 * 512 + k * 512 + h * 128 + cc]; }
;             bbs[0] = *(const f32x2*)(P.b_gk_f + l * 512 + h * 128 + c0); bbs[1] = *(const f32x2*)(P.b_gk_b + l * 512 + h * 128 + c0); }
;         *(LAS f32x4*)(lds + PP_LR + tid * 16) = n_lr;
	v_bitop3_b32 v7, v15, v16, 3 bitop3:0x36
	v_lshl_or_b32 v44, v7, 4, v17
	v_lshrrev_b32_e32 v7, 10, v76
	v_lshl_add_u32 v80, v7, 14, 0
	v_mul_u32_u24_e32 v46, 0xa00, v7
	v_lshrrev_b32_e32 v7, 10, v81
	v_lshl_add_u32 v82, v7, 14, 0
	v_mul_u32_u24_e32 v48, 0xa00, v7
	v_bitop3_b32 v7, v65, v12, 7 bitop3:0x6c
	v_lshlrev_b32_e32 v50, 4, v7
	v_lshrrev_b32_e32 v7, 8, v76
	v_lshlrev_b32_e32 v84, 12, v7
	v_bitop3_b32 v7, v7, v65, 7 bitop3:0x78
	v_lshlrev_b32_e32 v52, 4, v7
	v_or_b32_e32 v7, 4, v12
	v_lshlrev_b32_e32 v85, 12, v7
	v_bitop3_b32 v7, v12, v16, 4 bitop3:0x36
	v_lshl_add_u64 v[12:13], s[80:81], 0, v[24:25]
	s_ashr_i32 s80, s33, 2
	s_ashr_i32 s81, s80, 31
	s_lshl_b64 s[82:83], s[80:81], 18
	v_lshl_add_u64 v[12:13], v[12:13], 0, s[82:83]
	v_lshl_add_u64 v[12:13], v[12:13], 0, v[56:57]
	s_lshl_b64 s[80:81], s[80:81], 13
	v_add_co_u32_e32 v14, vcc, s65, v12
	s_add_u32 s44, s44, s80
	s_nop 0
	v_addc_co_u32_e32 v15, vcc, 0, v13, vcc
	s_movk_i32 s65, 0x2000
	s_addc_u32 s45, s45, s81
	v_add_co_u32_e32 v16, vcc, s65, v12
	v_lshlrev_b32_e32 v54, 4, v7
	s_nop 0
	v_addc_co_u32_e32 v17, vcc, 0, v13, vcc
	global_load_dwordx4 v[18:21], v22, s[44:45]
	global_load_dword v177, v[16:17], off offset:-4096
	global_load_dword v179, v[16:17], off
	global_load_dword v180, v[16:17], off offset:1024
	s_movk_i32 s44, 0x3000
	v_add_co_u32_e32 v16, vcc, s44, v12
	s_movk_i32 s44, 0x4000
	s_nop 0
	v_addc_co_u32_e32 v17, vcc, 0, v13, vcc
	v_add_co_u32_e32 v58, vcc, s44, v12
	s_movk_i32 s44, 0x5000
	s_nop 0
	v_addc_co_u32_e32 v59, vcc, 0, v13, vcc
	v_add_co_u32_e32 v60, vcc, s44, v12
	s_movk_i32 s44, 0x6000
	s_nop 0
	v_addc_co_u32_e32 v61, vcc, 0, v13, vcc
	v_add_co_u32_e32 v62, vcc, s44, v12
	s_movk_i32 s44, 0x7000
	s_nop 0
	v_addc_co_u32_e32 v63, vcc, 0, v13, vcc
	global_load_dword v188, v[58:59], off offset:-4096
	global_load_dword v189, v[58:59], off
	global_load_dword v190, v[58:59], off offset:1024
	global_load_dword v196, v[62:63], off offset:-4096
	global_load_dword v204, v[62:63], off
	global_load_dword v205, v[62:63], off offset:1024
	v_add_co_u32_e32 v58, vcc, s44, v12
	v_lshrrev_b32_e32 v7, 8, v81
	s_nop 0
	v_addc_co_u32_e32 v59, vcc, 0, v13, vcc
	global_load_dword v181, v[12:13], off
	global_load_dword v182, v[12:13], off offset:1024
	global_load_dword v195, v[14:15], off offset:1024
	global_load_dword v199, v[16:17], off offset:1024
	global_load_dword v212, v[60:61], off offset:1024
	global_load_dword v216, v[58:59], off
	global_load_dword v217, v[58:59], off offset:1024
	v_lshlrev_b32_e32 v12, 12, v7
	v_bitop3_b32 v7, v7, v65, 7 bitop3:0x78
	v_lshlrev_b32_e32 v58, 4, v7
	v_mov_b32_e32 v7, v25
	v_lshl_add_u64 v[60:61], s[54:55], 0, v[6:7]
	v_lshl_add_u64 v[62:63], s[58:59], 0, v[6:7]
	v_lshl_add_u64 v[6:7], s[50:51], 0, v[6:7]
	s_mov_b64 s[44:45], 0x3b670000
	v_lshl_add_u64 v[64:65], v[6:7], 0, s[44:45]
	v_lshl_add_u64 v[6:7], s[50:51], 0, v[22:23]
	s_mov_b64 s[44:45], 0x30270000
	v_lshl_add_u64 v[70:71], v[6:7], 0, s[44:45]
	s_mov_b64 s[44:45], 0x36670000
	v_lshl_add_u64 v[74:75], v[4:5], 0, s[44:45]
	v_lshlrev_b32_e32 v4, 2, v76
	s_movk_i32 s54, 0x1e00
	v_and_or_b32 v184, v4, s54, v78
	v_add_u32_e32 v185, s70, v4
	v_or_b32_e32 v4, 0x1000, v3
	v_and_or_b32 v186, v4, s54, v78
	v_add_u32_e32 v187, s70, v4
	v_mov_b32_e32 v4, s57
	v_mov_b32_e32 v5, s53
	v_cmp_gt_u32_e32 vcc, s64, v136
	v_lshlrev_b32_e32 v8, 4, v76
	s_movk_i32 s44, 0xe00
	v_cndmask_b32_e32 v77, v4, v5, vcc
	v_mov_b32_e32 v4, s56
	v_mov_b32_e32 v5, s52
	v_cndmask_b32_e32 v76, v4, v5, vcc
	v_lshlrev_b32_e32 v4, 2, v81
	v_and_or_b32 v191, v4, s54, v78
	v_add_u32_e32 v192, s70, v4
	v_add_u32_e32 v4, 0x2800, v3
	v_and_or_b32 v193, v4, s54, v78
	v_add_u32_e32 v194, s70, v4
	v_or_b32_e32 v4, 0xc00, v136
	v_and_or_b32 v23, v3, s44, v78
	v_lshlrev_b32_e32 v5, 2, v4
	v_add_u32_e32 v3, 0x3800, v3
	v_and_or_b32 v197, v5, s54, v78
	v_and_or_b32 v201, v3, s54, v78
	v_lshlrev_b32_e32 v78, 1, v2
	v_mbcnt_lo_u32_b32 v2, -1, 0
	v_and_b32_e32 v8, 0x3ff0, v8
	v_mov_b32_e32 v24, v25
	v_mbcnt_hi_u32_b32 v213, -1, v2
	v_mov_b32_e32 v2, 0x80
	v_mov_b32_e32 v59, v25
	v_lshl_add_u64 v[68:69], s[78:79], 0, v[8:9]
	v_add_u32_e32 v198, s70, v5
	v_cmp_gt_u32_e64 s[44:45], s44, v4
	v_add_u32_e32 v203, s70, v3
	s_mov_b32 s70, -1
	s_mov_b64 s[54:55], 0x800
	s_mov_b64 s[58:59], 0x29e76000
	s_mov_b64 s[78:79], 0x29e74000
	v_add_u32_e32 v206, v80, v8
	v_add_u32_e32 v207, v82, v10
	v_add_u32_e32 v209, v79, v84
	v_add_u32_e32 v210, v79, v85
	v_add_u32_e32 v211, v79, v12
	v_lshl_or_b32 v214, v213, 2, v2
	v_mov_b64_e32 v[82:83], v[24:25]
	v_mov_b64_e32 v[80:81], v[24:25]
	s_mov_b32 s80, s33
	s_waitcnt vmcnt(0)
	s_branch .LBB0_898

; #define LAS __attribute__((address_space(3)))
; DI void phase_gla_prep(const Params& P, int l, int bid, int nb, LAS unsigned char* lds) {
;     ...
;     for (int task = bid; task < 2560; task += nb) {
;         const int c = task >> 2, h = task & 3;
;         __syncthreads();
;         if (h != hcur) { hcur = h;
;             for (int e = tid; e < 2 * 16 * 128; e += NTHR) { const int dir = e >> 11, k = (e >> 7) & 15, cc = e & 127;
;                 ((LAS float*)(lds + PP_W))[e] = (dir ? P.w_gk_b : P.w_gk_f)[(size_t)l * 16 * 512 + k * 512 + h * 128 + cc]; }
;             bbs[0] = *(const f32x2*)(P.b_gk_f + l * 512 + h * 128 + c0); bbs[1] = *(const f32x2*)(P.b_gk_b + l * 512 + h * 128 + c0); }
.LBB0_898:
	s_and_b32 s71, s80, 3
	s_cmp_eq_u32 s71, s70
	s_waitcnt vmcnt(16)
	s_barrier
	s_cbranch_scc1 .LBB0_902
	s_lshl_b32 s70, s71, 7
	v_or_b32_e32 v2, s70, v23
	v_lshlrev_b32_e32 v24, 2, v2
	v_lshl_add_u64 v[2:3], s[52:53], 0, v[24:25]
	v_or_b32_e32 v4, s70, v184
	v_add_co_u32_e32 v2, vcc, 0x8000, v2
	v_lshlrev_b32_e32 v4, 2, v4
	v_mov_b32_e32 v5, v25
	v_addc_co_u32_e32 v3, vcc, 0, v3, vcc
	v_lshl_add_u64 v[4:5], s[52:53], 0, v[4:5]
	v_or_b32_e32 v6, s70, v186
	v_add_co_u32_e32 v4, vcc, 0x8000, v4
	v_lshlrev_b32_e32 v6, 2, v6
	v_mov_b32_e32 v7, v25
	v_addc_co_u32_e32 v5, vcc, 0, v5, vcc
	v_lshl_add_u64 v[6:7], s[52:53], 0, v[6:7]
	v_add_co_u32_e32 v6, vcc, 0x8000, v6
	s_nop 1
	v_addc_co_u32_e32 v7, vcc, 0, v7, vcc
	global_load_dword v8, v[2:3], off
	global_load_dword v9, v[4:5], off
	global_load_dword v10, v[6:7], off
	v_or_b32_e32 v2, s70, v191
	v_lshlrev_b32_e32 v2, 2, v2
	v_mov_b32_e32 v3, v25
	v_lshl_add_u64 v[2:3], v[76:77], 0, v[2:3]
	v_add_co_u32_e32 v2, vcc, 0x8000, v2
	v_or_b32_e32 v4, s70, v193
	s_nop 0
	v_addc_co_u32_e32 v3, vcc, 0, v3, vcc
	global_load_dword v11, v[2:3], off
	v_lshl_add_u64 v[2:3], s[56:57], 0, v[24:25]
	v_add_co_u32_e32 v2, vcc, 0x8000, v2
	v_lshlrev_b32_e32 v24, 2, v4
	s_nop 0
	v_addc_co_u32_e32 v3, vcc, 0, v3, vcc
	v_lshl_add_u64 v[4:5], s[56:57], 0, v[24:25]
	v_or_b32_e32 v6, s70, v197
	v_add_co_u32_e32 v4, vcc, 0x8000, v4
	v_lshlrev_b32_e32 v24, 2, v6
	s_nop 0
	v_addc_co_u32_e32 v5, vcc, 0, v5, vcc
	v_lshl_add_u64 v[6:7], s[56:57], 0, v[24:25]
	v_add_co_u32_e32 v6, vcc, 0x8000, v6
	s_nop 1
	v_addc_co_u32_e32 v7, vcc, 0, v7, vcc
	global_load_dword v2, v[2:3], off
	s_nop 0
	global_load_dword v3, v[4:5], off
	s_nop 0
	global_load_dword v4, v[6:7], off
	s_waitcnt vmcnt(5)
	ds_write_b32 v185, v9
	s_waitcnt vmcnt(4)
	ds_write_b32 v187, v10
	s_waitcnt vmcnt(3)
	ds_write_b32 v192, v11
	s_waitcnt vmcnt(2)
	ds_write2st64_b32 v183, v8, v2 offset1:32
	s_waitcnt vmcnt(1)
	ds_write_b32 v194, v3
	s_waitcnt vmcnt(0)
	ds_write_b32 v198, v4
	s_and_saveexec_b64 s[82:83], s[44:45]
	s_cbranch_execz .LBB0_901
	v_or_b32_e32 v2, s70, v201
	v_lshlrev_b32_e32 v24, 2, v2
	v_lshl_add_u64 v[2:3], s[56:57], 0, v[24:25]
	v_add_co_u32_e32 v2, vcc, 0x8000, v2
	s_nop 1
	v_addc_co_u32_e32 v3, vcc, 0, v3, vcc
	global_load_dword v2, v[2:3], off
	s_waitcnt vmcnt(0)
	ds_write_b32 v203, v2

; #define LAS __attribute__((address_space(3)))
; DI float logsigmoid_fast(float z) { return fminf(z, 0.f) - 0.6931471805599453f * __builtin_amdgcn_logf(1.0f + __builtin_amdgcn_exp2f(-fabsf(z) * LOG2E)); }
; DI void phase_gla_prep(const Params& P, int l, int bid, int nb, LAS unsigned char* lds) {
;     ...
;         asm volatile("s_waitcnt lgkmcnt(0)" ::: "memory"); __builtin_amdgcn_s_barrier(); asm volatile("" ::: "memory");
; #pragma unroll 1
;         for (int dir = 0; dir < 2; ++dir) {
;             float w0[16], w1[16];
; #pragma unroll
;             for (int k = 0; k < 16; ++k) { const f32x2 t = *(const LAS f32x2*)(lds + PP_W + ((dir * 16 + k) * 128 + c0) * 4); w0[k] = t.x; w1[k] = t.y; }
;             const f32x2 bb = dir ? bbs[1] : bbs[0];
;             float g0[8], g1[8];
; #pragma unroll
;             for (int r = 0; r < 8; ++r) { float z0 = bb.x, z1 = bb.y; const LAS float* lr = (const LAS float*)(lds + PP_LR) + (rg * 8 + r) * 32 + dir * 16;
; #pragma unroll
;                 for (int k4 = 0; k4 < 4; ++k4) { const f32x4 t = *(const LAS f32x4*)(lr + k4 * 4);
; #pragma unroll
;                     for (int u = 0; u < 4; ++u) { z0 += t[u] * w0[k4 * 4 + u]; z1 += t[u] * w1[k4 * 4 + u]; } }
;                 g0[r] = logsigmoid_fast(z0) * 0.0625f; g1[r] = logsigmoid_fast(z1) * 0.0625f; __builtin_amdgcn_sched_barrier(0); }
;             float tot0, tot1;
;             if (dir == 0) {
; #pragma unroll
;                 for (int r = 1; r < 8; ++r) { g0[r] += g0[r - 1]; g1[r] += g1[r - 1]; }
;                 float s0 = g0[7], s1 = g1[7];
; #pragma unroll
;                 for (int o = 8; o < 64; o <<= 1) { const float t0 = __shfl_up(s0, o), t1 = __shfl_up(s1, o); if (lane >= o) { s0 += t0; s1 += t1; } }
;                 const float e0 = s0 - g0[7], e1 = s1 - g1[7];
; #pragma unroll
;                 for (int r = 0; r < 8; ++r) { g0[r] += e0; g1[r] += e1; }
;                 tot0 = __shfl(s0, 56 + dpl); tot1 = __shfl(s1, 56 + dpl);
;             } else {
; #pragma unroll
;                 for (int r = 6; r >= 0; --r) { g0[r] += g0[r + 1]; g1[r] += g1[r + 1]; }
;                 float s0 = g0[0], s1 = g1[0];
; #pragma unroll
;                 for (int o = 8; o < 64; o <<= 1) { const float t0 = __shfl_down(s0, o), t1 = __shfl_down(s1, o); if (lane + o < 64) { s0 += t0; s1 += t1; } }
.LBB0_904:
	v_lshlrev_b32_e32 v114, 16, v2
	v_and_b32_e32 v115, 0xffff0000, v2
	v_and_b32_e32 v2, 63, v213
	v_cmp_gt_u32_e32 vcc, 56, v2
	v_lshlrev_b32_e32 v108, 16, v3
	v_and_b32_e32 v109, 0xffff0000, v3
	v_cndmask_b32_e64 v3, 0, 8, vcc
	v_cmp_gt_u32_e32 vcc, 48, v2
	v_add_lshl_u32 v79, v3, v213, 2
	s_waitcnt lgkmcnt(0)
	s_barrier
	v_cndmask_b32_e64 v2, 0, 16, vcc
	v_add_lshl_u32 v218, v2, v213, 2
	v_and_b32_e32 v2, 64, v213
	v_or_b32_e32 v3, v2, v138
	v_lshlrev_b32_e32 v219, 2, v3
	v_add_u32_e32 v3, -8, v213
	v_cmp_lt_i32_e32 vcc, v3, v2
	s_ashr_i32 s81, s80, 31
	v_lshlrev_b32_e32 v84, 16, v17
	v_cndmask_b32_e32 v3, v3, v213, vcc
	v_lshlrev_b32_e32 v220, 2, v3
	v_add_u32_e32 v3, -16, v213
	v_cmp_lt_i32_e32 vcc, v3, v2
	v_and_b32_e32 v85, 0xffff0000, v17
	v_lshlrev_b32_e32 v86, 16, v15
	v_cndmask_b32_e32 v3, v3, v213, vcc
	v_lshlrev_b32_e32 v221, 2, v3
	v_subrev_u32_e32 v3, 32, v213
	v_cmp_lt_i32_e32 vcc, v3, v2
	v_and_b32_e32 v87, 0xffff0000, v15
	v_lshlrev_b32_e32 v88, 16, v13
	v_cndmask_b32_e32 v2, v3, v213, vcc
	v_and_b32_e32 v89, 0xffff0000, v13
	v_lshlrev_b32_e32 v90, 16, v16
	v_and_b32_e32 v91, 0xffff0000, v16
	v_lshlrev_b32_e32 v92, 16, v14
	v_and_b32_e32 v93, 0xffff0000, v14
	v_lshlrev_b32_e32 v94, 16, v12
	v_and_b32_e32 v95, 0xffff0000, v12
	v_lshlrev_b32_e32 v96, 16, v11
	v_and_b32_e32 v97, 0xffff0000, v11
	v_lshlrev_b32_e32 v98, 16, v9
	v_and_b32_e32 v99, 0xffff0000, v9
	v_lshlrev_b32_e32 v100, 16, v7
	v_and_b32_e32 v101, 0xffff0000, v7
	v_lshlrev_b32_e32 v102, 16, v10
	v_and_b32_e32 v103, 0xffff0000, v10
	v_lshlrev_b32_e32 v104, 16, v8
	v_and_b32_e32 v105, 0xffff0000, v8
	v_lshlrev_b32_e32 v106, 16, v5
	v_and_b32_e32 v107, 0xffff0000, v5
	v_lshlrev_b32_e32 v110, 16, v6
	v_and_b32_e32 v111, 0xffff0000, v6
	v_lshlrev_b32_e32 v112, 16, v4
	v_and_b32_e32 v113, 0xffff0000, v4
	s_mov_b32 s76, 0
	v_lshlrev_b32_e32 v222, 2, v2
	v_or_b32_e32 v223, 0xe0, v219
	s_mov_b64 s[84:85], -1
	s_cmp_lg_u32 s82, 0
	s_cbranch_scc1 .Lgp_full_1
	s_waitcnt vmcnt(17)
	s_branch .LBB0_906
